# attention: fast bias-table path for t=7,8 + lazy softmax rescale (8 log2 units) + QK wait pairs; GLA chunk-local unit: the four V-tile loads issued together before one wait
# speedup vs baseline: 1.0306x; 1.0131x over previous
; #define LAS __attribute__((address_space(3)))
; __device__ __forceinline__ int crow(int r, int hi) { return (r & 3) + 8 * (r >> 2) + 4 * hi; }
; __device__ __forceinline__ void attn_block_unit(LAS unsigned char* lds, const bf16* QB, bf16* OB, const bf16* KB, const bf16* VB, int sb, int hp, int cp, const float* tab, int tid) {
;     ...
;             LAS const unsigned char* kb = lds + (j & 1) * AB_BUF + hsel * AB_HB; LAS const unsigned char* vb = kb + 9216;
;             f32x16 s0, s1;
; #pragma unroll
;             for (int r = 0; r < 16; ++r) { s0[r] = 0.f; s1[r] = 0.f; }
; #pragma unroll
;             for (int d0 = 0; d0 < 4; ++d0) {
;                 const bf16x8 k0 = *(const LAS bf16x8*)(kb + r32 * ATT_VP + (16 * d0 + 8 * hi) * 2), k1 = *(const LAS bf16x8*)(kb + (32 + r32) * ATT_VP + (16 * d0 + 8 * hi) * 2);
;                 s0 = __builtin_amdgcn_mfma_f32_32x32x16_bf16(k0, qfr[d0], s0, 0, 0, 0); s1 = __builtin_amdgcn_mfma_f32_32x32x16_bf16(k1, qfr[d0], s1, 0, 0, 0); }
;             if (t < 6) {
; #pragma unroll
;                 for (int r = 0; r < 16; ++r) { s0[r] += cb; s1[r] += cb; }
;             } else {
;                 const int relb = 64 * (8 - t) + 32 * qh + r32 + 128;
; #pragma unroll
;                 for (int r = 0; r < 16; ++r) { const int i0 = relb - crow(r, hi); s0[r] += btab[i0 > 256 ? 256 : i0]; const int i1 = i0 - 32; s1[r] += btab[i1 > 256 ? 256 : i1]; }
;             }
.LBB0_550:
	s_bitcmp1_b32 s6, 0
	s_cselect_b32 s26, 0x9000, 0
	s_add_i32 s30, s28, s26
	v_add3_u32 v2, s30, v167, v138
	ds_read_b128 v[36:39], v2
	ds_read_b128 v[52:55], v2 offset:4608
	ds_read_b128 v[40:43], v2 offset:32
	ds_read_b128 v[56:59], v2 offset:4640
	ds_read_b128 v[44:47], v2 offset:64
	ds_read_b128 v[60:63], v2 offset:4672
	ds_read_b128 v[48:51], v2 offset:96
	ds_read_b128 v[64:67], v2 offset:4704
	v_add3_u32 v2, s30, v161, v163
	s_waitcnt lgkmcnt(6)
	v_mfma_f32_32x32x16_bf16 v[84:99], v[36:39], v[104:107], 0
	v_mfma_f32_32x32x16_bf16 v[68:83], v[52:55], v[104:107], 0
	s_waitcnt lgkmcnt(4)
	v_mfma_f32_32x32x16_bf16 v[84:99], v[40:43], v[108:111], v[84:99]
	v_mfma_f32_32x32x16_bf16 v[68:83], v[56:59], v[108:111], v[68:83]
	s_waitcnt lgkmcnt(2)
	v_mfma_f32_32x32x16_bf16 v[84:99], v[44:47], v[120:123], v[84:99]
	v_mfma_f32_32x32x16_bf16 v[68:83], v[60:63], v[120:123], v[68:83]
	s_waitcnt lgkmcnt(0)
	v_mfma_f32_32x32x16_bf16 v[84:99], v[48:51], v[124:127], v[84:99]
	v_mfma_f32_32x32x16_bf16 v[68:83], v[64:67], v[124:127], v[68:83]
	ds_read_b64_tr_b16 v[218:219], v2 offset:9216
	ds_read_b64_tr_b16 v[220:221], v2 offset:10368
	ds_read_b64_tr_b16 v[222:223], v2 offset:11520
	ds_read_b64_tr_b16 v[224:225], v2 offset:12672
	ds_read_b64_tr_b16 v[226:227], v2 offset:13824
	ds_read_b64_tr_b16 v[228:229], v2 offset:14976
	ds_read_b64_tr_b16 v[230:231], v2 offset:16128
	ds_read_b64_tr_b16 v[232:233], v2 offset:17280
	ds_read_b64_tr_b16 v[234:235], v2 offset:9280
	ds_read_b64_tr_b16 v[236:237], v2 offset:10432
	ds_read_b64_tr_b16 v[238:239], v2 offset:11584
	ds_read_b64_tr_b16 v[240:241], v2 offset:12736
	ds_read_b64_tr_b16 v[242:243], v2 offset:13888
	ds_read_b64_tr_b16 v[244:245], v2 offset:15040
	ds_read_b64_tr_b16 v[246:247], v2 offset:16192
	ds_read_b64_tr_b16 v[248:249], v2 offset:17344
	s_cmp_gt_u32 s31, 5
	s_cbranch_scc0 .Latt_t_lt6
	s_cmp_eq_u32 s31, 6
	s_cbranch_scc1 .Latt_t_eq6
	v_add_u32_e32 v2, v135, v213
	s_add_i32 s26, s2, 0x914
	v_add_u32_e32 v67, v135, v189
	v_lshl_add_u32 v2, v2, 2, s26
	v_lshl_add_u32 v67, v67, 2, s26
	ds_read_b32 v36, v2 offset:236
	ds_read_b32 v37, v2 offset:232
	ds_read_b32 v38, v67 offset:228
	ds_read_b32 v39, v67 offset:224
	ds_read_b32 v40, v67 offset:204
	ds_read_b32 v41, v67 offset:200
	ds_read_b32 v42, v67 offset:196
	ds_read_b32 v43, v67 offset:192
	ds_read_b32 v44, v67 offset:172
	ds_read_b32 v45, v67 offset:168
	ds_read_b32 v46, v67 offset:164
	ds_read_b32 v47, v67 offset:160
	ds_read_b32 v48, v67 offset:140
	ds_read_b32 v49, v67 offset:136
	ds_read_b32 v50, v67 offset:132
	ds_read_b32 v51, v67 offset:128
	ds_read_b32 v52, v2 offset:108
	ds_read_b32 v53, v2 offset:104
	ds_read_b32 v54, v67 offset:100
	ds_read_b32 v55, v67 offset:96
	ds_read_b32 v56, v67 offset:76
	ds_read_b32 v57, v67 offset:72
	ds_read_b32 v58, v67 offset:68
	ds_read_b32 v59, v67 offset:64
	ds_read_b32 v60, v67 offset:44
	ds_read_b32 v61, v67 offset:40
	ds_read_b32 v62, v67 offset:36
	ds_read_b32 v63, v67 offset:32
	ds_read_b32 v64, v67 offset:12
	ds_read_b32 v65, v67 offset:8
	ds_read_b32 v66, v67 offset:4
	ds_read_b32 v67, v67 offset:0
	s_waitcnt lgkmcnt(0)
	v_pk_add_f32 v[84:85], v[84:85], v[36:37]
	v_pk_add_f32 v[86:87], v[86:87], v[38:39]
	v_pk_add_f32 v[88:89], v[88:89], v[40:41]
	v_pk_add_f32 v[90:91], v[90:91], v[42:43]
	v_pk_add_f32 v[92:93], v[92:93], v[44:45]
	v_pk_add_f32 v[94:95], v[94:95], v[46:47]
	v_pk_add_f32 v[96:97], v[96:97], v[48:49]
	v_pk_add_f32 v[98:99], v[98:99], v[50:51]
	v_pk_add_f32 v[68:69], v[68:69], v[52:53]
	v_pk_add_f32 v[70:71], v[70:71], v[54:55]
	v_pk_add_f32 v[72:73], v[72:73], v[56:57]
	v_pk_add_f32 v[74:75], v[74:75], v[58:59]
	v_pk_add_f32 v[76:77], v[76:77], v[60:61]
	v_pk_add_f32 v[78:79], v[78:79], v[62:63]
	v_pk_add_f32 v[80:81], v[80:81], v[64:65]
	v_pk_add_f32 v[82:83], v[82:83], v[66:67]
	v_mov_b32_e32 v66, 0
	s_branch .Latt_softmax
; __device__ __forceinline__ int crow(int r, int hi) { return (r & 3) + 8 * (r >> 2) + 4 * hi; }
; __device__ __forceinline__ void attn_block_unit(LAS unsigned char* lds, const bf16* QB, bf16* OB, const bf16* KB, const bf16* VB, int sb, int hp, int cp, const float* tab, int tid) {
;     ...
;             } else {
;                 const int relb = 64 * (8 - t) + 32 * qh + r32 + 128;
; #pragma unroll
;                 for (int r = 0; r < 16; ++r) { const int i0 = relb - crow(r, hi); s0[r] += btab[i0 > 256 ? 256 : i0]; const int i1 = i0 - 32; s1[r] += btab[i1 > 256 ? 256 : i1]; }
;             }
.Latt_t_eq6:
	v_add_u32_e32 v2, v135, v213
	v_add_u32_e32 v36, 0x280, v2
	v_min_i32_e32 v37, 0x100, v36
	v_min_i32_e32 v36, 0x120, v36
	v_lshl_add_u32 v36, v36, 2, s2
	v_add_u32_e32 v2, 0x27f, v2
	v_add_u32_e32 v38, 0xffffff80, v36
	v_min_i32_e32 v36, 0x100, v2
	v_add_u32_e32 v48, v135, v189
	v_lshl_add_u32 v39, v36, 2, s2
	v_add_u32_e32 v36, 0x27e, v48
	v_min_i32_e32 v40, 0x100, v36
	v_min_i32_e32 v36, 0x120, v36
	v_lshl_add_u32 v36, v36, 2, s2
	v_add_u32_e32 v41, 0xffffff80, v36
	v_add_u32_e32 v36, 0x27d, v48
	v_min_i32_e32 v2, 0x120, v2
	v_min_i32_e32 v42, 0x100, v36
	v_min_i32_e32 v36, 0x120, v36
	v_lshl_add_u32 v37, v37, 2, s2
	v_lshl_add_u32 v2, v2, 2, s2
	v_lshl_add_u32 v36, v36, 2, s2
	v_add_u32_e32 v2, 0xffffff80, v2
	v_lshl_add_u32 v40, v40, 2, s2
	v_lshl_add_u32 v42, v42, 2, s2
	v_add_u32_e32 v43, 0xffffff80, v36
	ds_read_b32 v36, v37
	ds_read_b32 v52, v38
	ds_read_b32 v37, v39
	ds_read_b32 v53, v2
	ds_read_b32 v38, v40
	ds_read_b32 v54, v41
	ds_read_b32 v39, v42
	ds_read_b32 v55, v43
	v_add_u32_e32 v41, 0x277, v48
	v_min_i32_e32 v42, 0x100, v41
	v_min_i32_e32 v41, 0x120, v41
	v_lshl_add_u32 v41, v41, 2, s2
	v_add_u32_e32 v43, 0xffffff80, v41
	v_add_u32_e32 v41, 0x276, v48
	v_min_i32_e32 v44, 0x100, v41
	v_min_i32_e32 v41, 0x120, v41
	v_lshl_add_u32 v41, v41, 2, s2
	v_add_u32_e32 v2, 0x278, v48
	v_add_u32_e32 v45, 0xffffff80, v41
	v_add_u32_e32 v41, 0x275, v48
	v_min_i32_e32 v40, 0x100, v2
	v_min_i32_e32 v2, 0x120, v2
	v_min_i32_e32 v46, 0x100, v41
	v_min_i32_e32 v41, 0x120, v41
	v_lshl_add_u32 v40, v40, 2, s2
	v_lshl_add_u32 v2, v2, 2, s2
	v_lshl_add_u32 v42, v42, 2, s2
	v_lshl_add_u32 v41, v41, 2, s2
	v_add_u32_e32 v2, 0xffffff80, v2
	v_lshl_add_u32 v44, v44, 2, s2
	v_lshl_add_u32 v46, v46, 2, s2
	v_add_u32_e32 v47, 0xffffff80, v41
	ds_read_b32 v40, v40
	ds_read_b32 v56, v2
	ds_read_b32 v41, v42
	ds_read_b32 v57, v43
	ds_read_b32 v42, v44
	ds_read_b32 v58, v45
	ds_read_b32 v43, v46
	ds_read_b32 v59, v47
	v_add_u32_e32 v45, 0x26f, v48
	v_min_i32_e32 v46, 0x100, v45
	v_min_i32_e32 v45, 0x120, v45
	v_lshl_add_u32 v45, v45, 2, s2
	v_add_u32_e32 v47, 0xffffff80, v45
	v_add_u32_e32 v45, 0x26e, v48
	v_min_i32_e32 v49, 0x100, v45
	v_min_i32_e32 v45, 0x120, v45
	v_lshl_add_u32 v45, v45, 2, s2
	v_add_u32_e32 v50, 0xffffff80, v45
	v_add_u32_e32 v45, 0x26d, v48
	v_add_u32_e32 v2, 0x270, v48
	v_min_i32_e32 v51, 0x100, v45
	v_min_i32_e32 v45, 0x120, v45
	v_min_i32_e32 v44, 0x100, v2
	v_min_i32_e32 v2, 0x120, v2
	v_lshl_add_u32 v45, v45, 2, s2
	v_lshl_add_u32 v44, v44, 2, s2
	v_lshl_add_u32 v2, v2, 2, s2
	v_lshl_add_u32 v46, v46, 2, s2
	v_add_u32_e32 v63, 0xffffff80, v45
	v_add_u32_e32 v2, 0xffffff80, v2
	v_lshl_add_u32 v49, v49, 2, s2
	v_lshl_add_u32 v51, v51, 2, s2
	ds_read_b32 v44, v44
	ds_read_b32 v60, v2
	ds_read_b32 v45, v46
	ds_read_b32 v61, v47
	ds_read_b32 v46, v49
	ds_read_b32 v62, v50
	ds_read_b32 v47, v51
	ds_read_b32 v63, v63
	v_add_u32_e32 v50, 0x267, v48
	v_min_i32_e32 v51, 0x100, v50
	v_min_i32_e32 v50, 0x120, v50
	v_lshl_add_u32 v50, v50, 2, s2
	v_add_u32_e32 v191, 0xffffff80, v50
	v_add_u32_e32 v50, 0x266, v48
	v_lshl_add_u32 v65, v51, 2, s2
	v_min_i32_e32 v51, 0x100, v50
	v_min_i32_e32 v50, 0x120, v50
	v_add_u32_e32 v2, 0x268, v48
	v_lshl_add_u32 v50, v50, 2, s2
	v_add_u32_e32 v48, 0x265, v48
	v_min_i32_e32 v49, 0x100, v2
	v_min_i32_e32 v2, 0x120, v2
	v_add_u32_e32 v66, 0xffffff80, v50
	v_min_i32_e32 v50, 0x100, v48
	v_min_i32_e32 v48, 0x120, v48
	v_lshl_add_u32 v49, v49, 2, s2
	v_lshl_add_u32 v2, v2, 2, s2
	v_lshl_add_u32 v51, v51, 2, s2
	v_lshl_add_u32 v67, v50, 2, s2
	v_lshl_add_u32 v48, v48, 2, s2
	v_add_u32_e32 v2, 0xffffff80, v2
	v_add_u32_e32 v216, 0xffffff80, v48
	ds_read_b32 v48, v49
	ds_read_b32 v64, v2
	ds_read_b32 v50, v51
	ds_read_b32 v51, v67
	ds_read_b32 v49, v65
	ds_read_b32 v67, v216
	ds_read_b32 v66, v66
	ds_read_b32 v65, v191
	s_waitcnt lgkmcnt(4)
	v_pk_add_f32 v[98:99], v[98:99], v[50:51]
	s_waitcnt lgkmcnt(3)
	v_pk_add_f32 v[96:97], v[96:97], v[48:49]
	v_pk_add_f32 v[94:95], v[94:95], v[46:47]
	v_pk_add_f32 v[92:93], v[92:93], v[44:45]
	v_pk_add_f32 v[90:91], v[90:91], v[42:43]
	v_pk_add_f32 v[88:89], v[88:89], v[40:41]
	v_pk_add_f32 v[86:87], v[86:87], v[38:39]
	v_pk_add_f32 v[84:85], v[84:85], v[36:37]
	s_waitcnt lgkmcnt(1)
	v_pk_add_f32 v[82:83], v[82:83], v[66:67]
	s_waitcnt lgkmcnt(0)
	v_pk_add_f32 v[80:81], v[80:81], v[64:65]
	v_pk_add_f32 v[78:79], v[78:79], v[62:63]
	v_pk_add_f32 v[76:77], v[76:77], v[60:61]
	v_pk_add_f32 v[74:75], v[74:75], v[58:59]
	v_pk_add_f32 v[72:73], v[72:73], v[56:57]
	v_pk_add_f32 v[70:71], v[70:71], v[54:55]
	v_pk_add_f32 v[68:69], v[68:69], v[52:53]
	v_mov_b32_e32 v66, 0
	s_branch .Latt_softmax

; #define LAS __attribute__((address_space(3)))
; __device__ __forceinline__ bf16x8 cat8(s16x4 a, s16x4 b) { return (bf16x8){a[0], a[1], a[2], a[3], b[0], b[1], b[2], b[3]}; }
; __device__ __forceinline__ bf16x8 pack8(const f32x16& v, int o) { u32x4 w; w.x = pk2(v[o], v[o + 1]); w.y = pk2(v[o + 2], v[o + 3]); w.z = pk2(v[o + 4], v[o + 5]); w.w = pk2(v[o + 6], v[o + 7]); return __builtin_bit_cast(bf16x8, w); }
; __device__ __forceinline__ void attn_block_unit(LAS unsigned char* lds, const bf16* QB, bf16* OB, const bf16* KB, const bf16* VB, int sb, int hp, int cp, const float* tab, int tid) {
;     ...
;             float tm = fmaxf(s0[0], s1[0]);
; #pragma unroll
;             for (int r = 1; r < 16; ++r) tm = fmaxf(tm, fmaxf(s0[r], s1[r]));
;             tm = fmaxf(tm, __shfl_xor(tm, 32));
;             const float mn = fmaxf(mrun, tm), sc = __expf(mrun - mn); mrun = mn;
;             float ps = 0.f;
; #pragma unroll
;             for (int r = 0; r < 16; ++r) { s0[r] = __expf(s0[r] - mn); s1[r] = __expf(s1[r] - mn); ps += s0[r] + s1[r]; }
;             lrun = lrun * sc + ps;
; #pragma unroll
;             for (int r = 0; r < 16; ++r) { oT[0][r] *= sc; oT[1][r] *= sc; }
;             bf16x8 pf[4]; pf[0] = pack8(s0, 0); pf[1] = pack8(s0, 8); pf[2] = pack8(s1, 0); pf[3] = pack8(s1, 8);
; #pragma unroll
;             for (int dh = 0; dh < 2; ++dh)
; #pragma unroll
;                 for (int kc = 0; kc < 4; ++kc) {
;                     LAS const unsigned char* p = vb + traddr + (16 * kc) * ATT_VP + dh * 64;
;                     const bf16x8 vf = cat8(tr16(p), tr16(p + 8 * ATT_VP));
;                     oT[dh] = __builtin_amdgcn_mfma_f32_32x32x16_bf16(vf, pf[kc], oT[dh], 0, 0, 0);
;                 }
.Latt_softmax:
	v_max3_f32 v36, v84, v85, v86
	v_max3_f32 v37, v87, v88, v89
	v_max3_f32 v38, v90, v91, v92
	v_max3_f32 v39, v93, v94, v95
	v_max3_f32 v40, v96, v97, v98
	v_max3_f32 v41, v99, v68, v69
	v_max3_f32 v42, v70, v71, v72
	v_max3_f32 v43, v73, v74, v75
	v_max3_f32 v44, v76, v77, v78
	v_max3_f32 v45, v79, v80, v81
	v_max3_f32 v46, v82, v83, v36
	v_max3_f32 v37, v37, v38, v39
	v_max3_f32 v40, v40, v41, v42
	v_max3_f32 v43, v43, v44, v45
	v_max3_f32 v37, v37, v40, v43
	v_max_f32_e32 v64, v37, v46
	ds_bpermute_b32 v65, v200, v64
	s_waitcnt lgkmcnt(0)
	v_max_f32_e32 v64, v64, v65
	v_add_f32_e32 v64, v64, v66
	v_sub_f32_e32 v63, v64, v215
	v_cmp_lt_f32_e32 vcc, 0x40b17218, v63
	s_cbranch_vccz .Latt_keep_max
	v_max_f32_e32 v67, v215, v64
	v_sub_f32_e32 v63, v215, v67
	v_mul_f32_e32 v63, 0x3fb8aa3b, v63
	v_exp_f32_e32 v52, v63
	v_mov_b32_e32 v215, v67
	v_pk_mul_f32 v[34:35], v[34:35], v[52:53] op_sel_hi:[1,0]
	v_pk_mul_f32 v[32:33], v[32:33], v[52:53] op_sel_hi:[1,0]
	v_pk_mul_f32 v[30:31], v[30:31], v[52:53] op_sel_hi:[1,0]
	v_pk_mul_f32 v[28:29], v[28:29], v[52:53] op_sel_hi:[1,0]
	v_pk_mul_f32 v[26:27], v[26:27], v[52:53] op_sel_hi:[1,0]
	v_pk_mul_f32 v[24:25], v[24:25], v[52:53] op_sel_hi:[1,0]
	v_pk_mul_f32 v[22:23], v[22:23], v[52:53] op_sel_hi:[1,0]
	v_pk_mul_f32 v[20:21], v[20:21], v[52:53] op_sel_hi:[1,0]
	v_pk_mul_f32 v[18:19], v[18:19], v[52:53] op_sel_hi:[1,0]
	v_pk_mul_f32 v[16:17], v[16:17], v[52:53] op_sel_hi:[1,0]
	v_pk_mul_f32 v[14:15], v[14:15], v[52:53] op_sel_hi:[1,0]
	v_pk_mul_f32 v[12:13], v[12:13], v[52:53] op_sel_hi:[1,0]
	v_pk_mul_f32 v[10:11], v[10:11], v[52:53] op_sel_hi:[1,0]
	v_pk_mul_f32 v[8:9], v[8:9], v[52:53] op_sel_hi:[1,0]
	v_pk_mul_f32 v[6:7], v[6:7], v[52:53] op_sel_hi:[1,0]
	v_pk_mul_f32 v[4:5], v[4:5], v[52:53] op_sel_hi:[1,0]
	v_mul_f32_e32 v214, v214, v52
.Latt_keep_max:
	v_sub_f32_e32 v62, v66, v215
	v_mul_f32_e32 v62, 0x3fb8aa3b, v62
	v_fmamk_f32 v84, v84, 0x3fb8aa3b, v62
	v_fmamk_f32 v85, v85, 0x3fb8aa3b, v62
	v_fmamk_f32 v86, v86, 0x3fb8aa3b, v62
	v_fmamk_f32 v87, v87, 0x3fb8aa3b, v62
	v_fmamk_f32 v88, v88, 0x3fb8aa3b, v62
	v_fmamk_f32 v89, v89, 0x3fb8aa3b, v62
	v_fmamk_f32 v90, v90, 0x3fb8aa3b, v62
	v_fmamk_f32 v91, v91, 0x3fb8aa3b, v62
	v_fmamk_f32 v92, v92, 0x3fb8aa3b, v62
	v_fmamk_f32 v93, v93, 0x3fb8aa3b, v62
	v_fmamk_f32 v94, v94, 0x3fb8aa3b, v62
	v_fmamk_f32 v95, v95, 0x3fb8aa3b, v62
	v_fmamk_f32 v96, v96, 0x3fb8aa3b, v62
	v_fmamk_f32 v97, v97, 0x3fb8aa3b, v62
	v_fmamk_f32 v98, v98, 0x3fb8aa3b, v62
	v_fmamk_f32 v99, v99, 0x3fb8aa3b, v62
	v_fmamk_f32 v68, v68, 0x3fb8aa3b, v62
	v_fmamk_f32 v69, v69, 0x3fb8aa3b, v62
	v_fmamk_f32 v70, v70, 0x3fb8aa3b, v62
	v_fmamk_f32 v71, v71, 0x3fb8aa3b, v62
	v_fmamk_f32 v72, v72, 0x3fb8aa3b, v62
	v_fmamk_f32 v73, v73, 0x3fb8aa3b, v62
	v_fmamk_f32 v74, v74, 0x3fb8aa3b, v62
	v_fmamk_f32 v75, v75, 0x3fb8aa3b, v62
	v_fmamk_f32 v76, v76, 0x3fb8aa3b, v62
	v_fmamk_f32 v77, v77, 0x3fb8aa3b, v62
	v_fmamk_f32 v78, v78, 0x3fb8aa3b, v62
	v_fmamk_f32 v79, v79, 0x3fb8aa3b, v62
	v_fmamk_f32 v80, v80, 0x3fb8aa3b, v62
	v_fmamk_f32 v81, v81, 0x3fb8aa3b, v62
	v_fmamk_f32 v82, v82, 0x3fb8aa3b, v62
	v_fmamk_f32 v83, v83, 0x3fb8aa3b, v62
	v_exp_f32_e32 v84, v84
	v_exp_f32_e32 v85, v85
	v_exp_f32_e32 v86, v86
	v_exp_f32_e32 v87, v87
	v_exp_f32_e32 v88, v88
	v_exp_f32_e32 v89, v89
	v_exp_f32_e32 v90, v90
	v_exp_f32_e32 v91, v91
	v_exp_f32_e32 v92, v92
	v_exp_f32_e32 v93, v93
	v_exp_f32_e32 v94, v94
	v_exp_f32_e32 v95, v95
	v_exp_f32_e32 v96, v96
	v_exp_f32_e32 v97, v97
	v_exp_f32_e32 v98, v98
	v_exp_f32_e32 v99, v99
	v_exp_f32_e32 v68, v68
	v_exp_f32_e32 v69, v69
	v_exp_f32_e32 v70, v70
	v_exp_f32_e32 v71, v71
	v_exp_f32_e32 v72, v72
	v_exp_f32_e32 v73, v73
	v_exp_f32_e32 v74, v74
	v_exp_f32_e32 v75, v75
	v_exp_f32_e32 v76, v76
	v_exp_f32_e32 v77, v77
	v_exp_f32_e32 v78, v78
	v_exp_f32_e32 v79, v79
	v_exp_f32_e32 v80, v80
	v_exp_f32_e32 v81, v81
	v_exp_f32_e32 v82, v82
	v_exp_f32_e32 v83, v83
	v_pk_add_f32 v[36:37], v[84:85], v[86:87]
	v_pk_add_f32 v[38:39], v[88:89], v[90:91]
	v_pk_add_f32 v[40:41], v[92:93], v[94:95]
	v_pk_add_f32 v[42:43], v[96:97], v[98:99]
	v_pk_add_f32 v[44:45], v[68:69], v[70:71]
	v_pk_add_f32 v[46:47], v[72:73], v[74:75]
	v_pk_add_f32 v[48:49], v[76:77], v[78:79]
	v_pk_add_f32 v[50:51], v[80:81], v[82:83]
	v_pk_add_f32 v[54:55], v[36:37], v[38:39]
	v_pk_add_f32 v[56:57], v[40:41], v[42:43]
	v_pk_add_f32 v[58:59], v[44:45], v[46:47]
	v_pk_add_f32 v[60:61], v[48:49], v[50:51]
	v_pk_add_f32 v[54:55], v[54:55], v[56:57]
	v_pk_add_f32 v[58:59], v[58:59], v[60:61]
	v_pk_add_f32 v[54:55], v[54:55], v[58:59]
	v_add_f32_e32 v54, v54, v55
	v_add_f32_e32 v214, v214, v54
	v_cvt_pk_bf16_f32 v36, v84, v85
	v_cvt_pk_bf16_f32 v37, v86, v87
	v_cvt_pk_bf16_f32 v38, v88, v89
	v_cvt_pk_bf16_f32 v39, v90, v91
	v_cvt_pk_bf16_f32 v40, v92, v93
	v_cvt_pk_bf16_f32 v41, v94, v95
	v_cvt_pk_bf16_f32 v42, v96, v97
	v_cvt_pk_bf16_f32 v43, v98, v99
	v_cvt_pk_bf16_f32 v44, v68, v69
	v_cvt_pk_bf16_f32 v45, v70, v71
	v_cvt_pk_bf16_f32 v46, v72, v73
	v_cvt_pk_bf16_f32 v47, v74, v75
	v_cvt_pk_bf16_f32 v48, v76, v77
	v_cvt_pk_bf16_f32 v49, v78, v79
	v_cvt_pk_bf16_f32 v50, v80, v81
	v_cvt_pk_bf16_f32 v51, v82, v83
	s_waitcnt lgkmcnt(0)
	v_mfma_f32_32x32x16_bf16 v[20:35], v[218:221], v[36:39], v[20:35]
	v_mfma_f32_32x32x16_bf16 v[4:19], v[234:237], v[36:39], v[4:19]
	v_mfma_f32_32x32x16_bf16 v[20:35], v[222:225], v[40:43], v[20:35]
	v_mfma_f32_32x32x16_bf16 v[4:19], v[238:241], v[40:43], v[4:19]
	v_mfma_f32_32x32x16_bf16 v[20:35], v[226:229], v[44:47], v[20:35]
	v_mfma_f32_32x32x16_bf16 v[4:19], v[242:245], v[44:47], v[4:19]
	v_mfma_f32_32x32x16_bf16 v[20:35], v[230:233], v[48:51], v[20:35]
	v_mfma_f32_32x32x16_bf16 v[4:19], v[246:249], v[48:51], v[4:19]
	s_andn2_b64 vcc, exec, s[14:15]
	s_add_i32 s14, s6, 1
	s_cbranch_vccz .LBB0_546
	s_branch .LBB0_547

; #define LAS __attribute__((address_space(3)))
; __device__ __forceinline__ void gla_a_unit(LAS unsigned char* lds, bf16* QKA, bf16* VA, const float* FA, unsigned char* ws, int xnrow0, float* DECB, int lchunk, int h,
;                                            const float* wgate, const float* bgate, int tid) {
;     const int lane = tid & 63, w = __builtin_amdgcn_readfirstlane(tid >> 6), r32 = lane & 31, hi = lane >> 5, g16 = lane >> 4, i16 = lane & 15;
;     const int gd = tid & 127, tq = tid >> 7;
;     LAS float* Bimg = (LAS float*)(lds + G_B); LAS float* FAi = (LAS float*)(lds + G_FA); LAS float* SEG = (LAS float*)(lds + G_SEG);
;     const int trrow = (g16 >> 1) * 4 + (i16 >> 2), trcol = (g16 & 1) * 16 + (i16 & 3) * 4;
;     const size_t row0 = (size_t)lchunk * 64; const int unit = lchunk * 4 + h;
;     u32x4 qv[2], kv[2];
; #pragma unroll
;     for (int i = 0; i < 2; ++i) { const int id = tid + 512 * i, row = id >> 4, ch = id & 15; const bf16* p = QKA + (row0 + row) * 1024 + h * 128 + ch * 8; qv[i] = *(const u32x4*)p; kv[i] = *(const u32x4*)(p + 512); }
;     if (tid < 256) *(LAS f32x4*)(FAi + tid * 4) = *(const f32x4*)(FA + row0 * 16 + tid * 4);
; #pragma unroll
;     for (int i = 0; i < 4; ++i) { const int id = tid + 512 * i, row = id >> 5, ch = id & 31; *(LAS u32x4*)(lds + G_VV + row * GVP + ch * 16) = *(const u32x4*)(VA + (row0 + row) * 1024 + h * 256 + ch * 8); }
;     __syncthreads();
;     {
;         float wg[16];
; #pragma unroll
;         for (int r = 0; r < 16; ++r) wg[r] = wgate[r * 512 + h * 128 + gd];
;         const float bg = bgate[h * 128 + gd];
;         float run = 0.f;
; #pragma unroll
;         for (int tt = 0; tt < 16; ++tt) { const int t = tq * 16 + tt; const LAS f32x4* fp = (const LAS f32x4*)(FAi + t * 16); float x = bg;
; #pragma unroll
;             for (int q = 0; q < 4; ++q) { const f32x4 f = fp[q]; x += f[0] * wg[4 * q] + f[1] * wg[4 * q + 1] + f[2] * wg[4 * q + 2] + f[3] * wg[4 * q + 3]; }
;             const float ls = fminf(x, 0.f) - __logf(1.0f + __expf(-fabsf(x))); run += ls * 0.0625f; Bimg[t * GBP + gd] = run;
.LBB0_558:
	s_mov_b32 s0, s66
	s_ashr_i32 s66, s3, 2
	s_mov_b32 s33, s67
	s_ashr_i32 s67, s66, 31
	s_and_b32 s97, s3, 3
	s_lshl_b64 s[82:83], s[66:67], 6
	s_lshl_b32 s78, s97, 8
	v_lshl_add_u64 v[6:7], s[82:83], 0, v[100:101]
	v_lshl_add_u64 v[4:5], v[118:119], 0, s[78:79]
	v_lshlrev_b64 v[6:7], 11, v[6:7]
	v_lshl_add_u64 v[62:63], v[4:5], 0, v[6:7]
	v_lshl_add_u64 v[6:7], s[82:83], 0, v[102:103]
	v_lshlrev_b64 v[6:7], 11, v[6:7]
	s_mov_b64 s[6:7], s[90:91]
	v_lshl_add_u64 v[60:61], v[4:5], 0, v[6:7]
	s_mov_b32 s69, s64
	s_mov_b32 s68, s70
	s_load_dwordx2 s[62:63], s[6:7], 0x50
	s_mov_b64 s[70:71], s[90:91]
	s_load_dwordx2 s[64:65], s[90:91], 0x58
	global_load_dwordx4 v[16:19], v[62:63], off
	global_load_dwordx4 v[12:15], v[62:63], off offset:1024
	global_load_dwordx4 v[8:11], v[60:61], off
	global_load_dwordx4 v[4:7], v[60:61], off offset:1024
	v_readfirstlane_b32 s2, v117
	s_lshl_b32 s96, s97, 7
	s_lshl_b32 s6, s97, 9
	s_mov_b32 s7, s79
	v_lshl_add_u64 v[24:25], v[106:107], 0, s[6:7]
	v_lshl_add_u64 v[20:21], s[82:83], 0, v[108:109]
	v_lshlrev_b64 v[20:21], 11, v[20:21]
	v_lshl_add_u64 v[20:21], v[24:25], 0, v[20:21]
	global_load_dwordx4 v[36:39], v[20:21], off
	v_lshl_add_u64 v[20:21], s[82:83], 0, v[110:111]
	v_lshlrev_b64 v[20:21], 11, v[20:21]
	v_lshl_add_u64 v[20:21], v[24:25], 0, v[20:21]
	global_load_dwordx4 v[40:43], v[20:21], off
	v_lshl_add_u64 v[20:21], s[82:83], 0, v[112:113]
	v_lshlrev_b64 v[20:21], 11, v[20:21]
	v_lshl_add_u64 v[20:21], v[24:25], 0, v[20:21]
	global_load_dwordx4 v[44:47], v[20:21], off
	v_lshl_add_u64 v[20:21], s[82:83], 0, v[114:115]
	v_lshlrev_b64 v[20:21], 11, v[20:21]
	v_lshl_add_u64 v[20:21], v[24:25], 0, v[20:21]
	global_load_dwordx4 v[48:51], v[20:21], off
	s_and_saveexec_b64 s[6:7], vcc
	s_cbranch_execz .LBB0_560
	s_lshl_b64 s[66:67], s[66:67], 12
	v_lshl_add_u64 v[20:21], v[104:105], 0, s[66:67]
	global_load_dwordx4 v[20:23], v[20:21], off
	s_waitcnt vmcnt(0)
	ds_write_b128 v127, v[20:23]
.LBB0_560:
	s_or_b64 exec, exec, s[6:7]
	s_lshl_b32 s6, s97, 9
	s_mov_b32 s7, s79
	v_or_b32_e32 v2, s96, v126
	v_lshlrev_b32_e32 v2, 2, v2
	s_waitcnt lgkmcnt(0)
	v_lshl_add_u64 v[34:35], s[62:63], 0, v[2:3]
	s_movk_i32 s97, 0x1000
	s_movk_i32 s96, 0x2000
	s_movk_i32 s6, 0x3000
	s_waitcnt vmcnt(0)
	ds_write_b128 v134, v[36:39] offset:34816
	ds_write_b128 v135, v[40:43] offset:34816
	ds_write_b128 v136, v[44:47] offset:34816
	ds_write_b128 v137, v[48:51] offset:34816
	s_waitcnt lgkmcnt(0)
	s_barrier
	global_load_dword v20, v2, s[62:63]
	global_load_dword v22, v2, s[62:63] offset:2048
	v_add_co_u32_e64 v26, s[62:63], s97, v34
	s_nop 1
	v_addc_co_u32_e64 v27, s[62:63], 0, v35, s[62:63]
	v_add_co_u32_e64 v28, s[62:63], s96, v34
	s_nop 1
	v_addc_co_u32_e64 v29, s[62:63], 0, v35, s[62:63]
	global_load_dword v25, v[28:29], off offset:-4096
	global_load_dword v23, v[26:27], off offset:2048
	global_load_dword v21, v[28:29], off
	global_load_dword v24, v[28:29], off offset:2048
	v_add_co_u32_e64 v26, s[62:63], s6, v34
	s_movk_i32 s6, 0x4000
	s_nop 0
	v_addc_co_u32_e64 v27, s[62:63], 0, v35, s[62:63]
	v_add_co_u32_e64 v30, s[62:63], s6, v34
	s_movk_i32 s6, 0x5000
	s_nop 0
	v_addc_co_u32_e64 v31, s[62:63], 0, v35, s[62:63]
	global_load_dword v29, v[30:31], off offset:-4096
	s_nop 0
	global_load_dword v27, v[26:27], off offset:2048
	s_nop 0
	global_load_dword v26, v[30:31], off
	global_load_dword v28, v[30:31], off offset:2048
	v_add_co_u32_e64 v30, s[62:63], s6, v34
	s_movk_i32 s6, 0x6000
	s_nop 0
	v_addc_co_u32_e64 v31, s[62:63], 0, v35, s[62:63]
	v_add_co_u32_e64 v36, s[62:63], s6, v34
	s_movk_i32 s6, 0x7000
	s_nop 0
	v_addc_co_u32_e64 v37, s[62:63], 0, v35, s[62:63]
	global_load_dword v33, v[36:37], off offset:-4096
	s_nop 0
	global_load_dword v31, v[30:31], off offset:2048
	s_nop 0
	global_load_dword v30, v[36:37], off
	global_load_dword v32, v[36:37], off offset:2048
	v_add_co_u32_e64 v36, s[62:63], s6, v34
	v_readlane_b32 s6, v251, 53
	s_nop 0
	v_addc_co_u32_e64 v37, s[62:63], 0, v35, s[62:63]
	global_load_dword v34, v[36:37], off
	global_load_dword v35, v[36:37], off offset:2048
	s_nop 0
	global_load_dword v2, v2, s[64:65]
	v_add_u32_e32 v48, s6, v128
	ds_read_b128 v[36:39], v48
	ds_read_b128 v[40:43], v48 offset:16
	ds_read_b128 v[44:47], v48 offset:32
	ds_read_b128 v[48:51], v48 offset:48
	s_mov_b32 s6, 0x3d800000
	s_waitcnt vmcnt(15) lgkmcnt(3)
	v_mul_f32_e32 v37, v22, v37
	v_fmac_f32_e32 v37, v20, v36
	s_waitcnt vmcnt(14)
	v_fmac_f32_e32 v37, v25, v38
	s_waitcnt vmcnt(13)
	v_fmac_f32_e32 v37, v23, v39
	s_waitcnt vmcnt(0)
	v_add_f32_e32 v36, v2, v37
	s_waitcnt lgkmcnt(2)
	v_mul_f32_e32 v37, v24, v41
	v_fmac_f32_e32 v37, v21, v40
	v_fmac_f32_e32 v37, v29, v42
	v_fmac_f32_e32 v37, v27, v43
	v_add_f32_e32 v36, v36, v37
	s_waitcnt lgkmcnt(1)
	v_mul_f32_e32 v37, v28, v45
	v_fmac_f32_e32 v37, v26, v44
	v_fmac_f32_e32 v37, v33, v46
	v_fmac_f32_e32 v37, v31, v47
	v_add_f32_e32 v36, v36, v37
	s_waitcnt lgkmcnt(0)
	v_mul_f32_e32 v37, v32, v49
	v_fmac_f32_e32 v37, v30, v48
	v_fmac_f32_e32 v37, v34, v50
	v_fmac_f32_e32 v37, v35, v51
	v_add_f32_e32 v36, v36, v37
	v_min_f32_e32 v37, 0, v36
	v_mul_f32_e64 v36, |v36|, s93
	v_exp_f32_e32 v36, v36
	s_nop 0
	v_add_f32_e32 v36, 1.0, v36
	v_cmp_gt_f32_e64 s[62:63], s92, v36
	s_nop 1
	v_cndmask_b32_e64 v38, 0, 32, s[62:63]
	v_ldexp_f32 v36, v36, v38
	v_log_f32_e32 v36, v36
	s_nop 0
	v_mul_f32_e32 v38, 0x3f317217, v36
	v_fma_f32 v38, v36, s1, -v38
	v_fmac_f32_e32 v38, 0x3377d1cf, v36
	v_fmac_f32_e32 v38, 0x3f317217, v36
	v_cmp_lt_f32_e64 s[64:65], |v36|, s72
	s_nop 1
	v_cndmask_b32_e64 v36, v36, v38, s[64:65]
	v_cndmask_b32_e64 v38, 0, v208, s[62:63]
	v_sub_f32_e32 v36, v36, v38
	v_sub_f32_e32 v36, v37, v36
	v_fma_f32 v36, v36, s6, 0
	ds_write_b32 v138, v36
	ds_read_b128 v[38:41], v154
	ds_read_b128 v[42:45], v154 offset:16
	ds_read_b128 v[46:49], v154 offset:32
	ds_read_b128 v[50:53], v154 offset:48
	s_mov_b64 s[6:7], 0x4200000
	s_waitcnt lgkmcnt(3)
; #define LAS __attribute__((address_space(3)))
; __device__ __forceinline__ void gla_a_unit(LAS unsigned char* lds, bf16* QKA, bf16* VA, const float* FA, unsigned char* ws, int xnrow0, float* DECB, int lchunk, int h,
;                                            const float* wgate, const float* bgate, int tid) {
;     ...
;         float wg[16];
; #pragma unroll
;         for (int r = 0; r < 16; ++r) wg[r] = wgate[r * 512 + h * 128 + gd];
;         const float bg = bgate[h * 128 + gd];
;         float run = 0.f;
; #pragma unroll
;         for (int tt = 0; tt < 16; ++tt) { const int t = tq * 16 + tt; const LAS f32x4* fp = (const LAS f32x4*)(FAi + t * 16); float x = bg;
; #pragma unroll
;             for (int q = 0; q < 4; ++q) { const f32x4 f = fp[q]; x += f[0] * wg[4 * q] + f[1] * wg[4 * q + 1] + f[2] * wg[4 * q + 2] + f[3] * wg[4 * q + 3]; }
;             const float ls = fminf(x, 0.f) - __logf(1.0f + __expf(-fabsf(x))); run += ls * 0.0625f; Bimg[t * GBP + gd] = run;
;             if ((tt & 3) == 3) asm volatile("" ::: "memory"); }
;         SEG[tq * 128 + gd] = run;
	v_mul_f32_e32 v37, v22, v39
	v_fmac_f32_e32 v37, v20, v38
	s_waitcnt lgkmcnt(2)
	v_mul_f32_e32 v38, v24, v43
	v_fmac_f32_e32 v37, v25, v40
	v_fmac_f32_e32 v38, v21, v42
	v_fmac_f32_e32 v37, v23, v41
	v_fmac_f32_e32 v38, v29, v44
	v_add_f32_e32 v37, v2, v37
	v_fmac_f32_e32 v38, v27, v45
	v_add_f32_e32 v37, v37, v38
	s_waitcnt lgkmcnt(1)
	v_mul_f32_e32 v38, v28, v47
	v_fmac_f32_e32 v38, v26, v46
	v_fmac_f32_e32 v38, v33, v48
	v_fmac_f32_e32 v38, v31, v49
	v_add_f32_e32 v37, v37, v38
	s_waitcnt lgkmcnt(0)
	v_mul_f32_e32 v38, v32, v51
	v_fmac_f32_e32 v38, v30, v50
	v_fmac_f32_e32 v38, v34, v52
	v_fmac_f32_e32 v38, v35, v53
	v_add_f32_e32 v37, v37, v38
	v_min_f32_e32 v38, 0, v37
	v_mul_f32_e64 v37, |v37|, s93
	v_exp_f32_e32 v37, v37
	s_nop 0
	v_add_f32_e32 v37, 1.0, v37
	v_cmp_gt_f32_e64 s[62:63], s92, v37
	s_nop 1
	v_cndmask_b32_e64 v39, 0, 32, s[62:63]
	v_ldexp_f32 v37, v37, v39
	v_log_f32_e32 v37, v37
	s_nop 0
	v_mul_f32_e32 v39, 0x3f317217, v37
	v_fma_f32 v39, v37, s1, -v39
	v_fmac_f32_e32 v39, 0x3377d1cf, v37
	v_fmac_f32_e32 v39, 0x3f317217, v37
	v_cmp_lt_f32_e64 s[64:65], |v37|, s72
	s_nop 1
	v_cndmask_b32_e64 v37, v37, v39, s[64:65]
	v_cndmask_b32_e64 v39, 0, v208, s[62:63]
	v_sub_f32_e32 v37, v37, v39
	v_sub_f32_e32 v37, v38, v37
	v_fmac_f32_e32 v36, 0x3d800000, v37
	ds_write_b32 v138, v36 offset:528
	ds_read_b128 v[38:41], v155
	ds_read_b128 v[42:45], v155 offset:16
	ds_read_b128 v[46:49], v155 offset:32
	ds_read_b128 v[50:53], v155 offset:48
	s_waitcnt lgkmcnt(3)
	v_mul_f32_e32 v37, v22, v39
	v_fmac_f32_e32 v37, v20, v38
	s_waitcnt lgkmcnt(2)
	v_mul_f32_e32 v38, v24, v43
	v_fmac_f32_e32 v37, v25, v40
	v_fmac_f32_e32 v38, v21, v42
	v_fmac_f32_e32 v37, v23, v41
	v_fmac_f32_e32 v38, v29, v44
	v_add_f32_e32 v37, v2, v37
	v_fmac_f32_e32 v38, v27, v45
	v_add_f32_e32 v37, v37, v38
	s_waitcnt lgkmcnt(1)
	v_mul_f32_e32 v38, v28, v47
	v_fmac_f32_e32 v38, v26, v46
	v_fmac_f32_e32 v38, v33, v48
	v_fmac_f32_e32 v38, v31, v49
	v_add_f32_e32 v37, v37, v38
	s_waitcnt lgkmcnt(0)
	v_mul_f32_e32 v38, v32, v51
	v_fmac_f32_e32 v38, v30, v50
	v_fmac_f32_e32 v38, v34, v52
	v_fmac_f32_e32 v38, v35, v53
	v_add_f32_e32 v37, v37, v38
	v_min_f32_e32 v38, 0, v37
	v_mul_f32_e64 v37, |v37|, s93
	v_exp_f32_e32 v37, v37
	s_nop 0
	v_add_f32_e32 v37, 1.0, v37
	v_cmp_gt_f32_e64 s[62:63], s92, v37
	s_nop 1
	v_cndmask_b32_e64 v39, 0, 32, s[62:63]
	v_ldexp_f32 v37, v37, v39
	v_log_f32_e32 v37, v37
	s_nop 0
	v_mul_f32_e32 v39, 0x3f317217, v37
	v_fma_f32 v39, v37, s1, -v39
	v_fmac_f32_e32 v39, 0x3377d1cf, v37
	v_fmac_f32_e32 v39, 0x3f317217, v37
	v_cmp_lt_f32_e64 s[64:65], |v37|, s72
	s_nop 1
	v_cndmask_b32_e64 v37, v37, v39, s[64:65]
	v_cndmask_b32_e64 v39, 0, v208, s[62:63]
	v_sub_f32_e32 v37, v37, v39
	v_sub_f32_e32 v37, v38, v37
	v_fmac_f32_e32 v36, 0x3d800000, v37
	ds_write_b32 v138, v36 offset:1056
	ds_read_b128 v[38:41], v156
	ds_read_b128 v[42:45], v156 offset:16
	ds_read_b128 v[46:49], v156 offset:32
	ds_read_b128 v[50:53], v156 offset:48
	s_waitcnt lgkmcnt(3)
	v_mul_f32_e32 v37, v22, v39
	v_fmac_f32_e32 v37, v20, v38
	s_waitcnt lgkmcnt(2)
	v_mul_f32_e32 v38, v24, v43
	v_fmac_f32_e32 v37, v25, v40
	v_fmac_f32_e32 v38, v21, v42
	v_fmac_f32_e32 v37, v23, v41
	v_fmac_f32_e32 v38, v29, v44
	v_add_f32_e32 v37, v2, v37
	v_fmac_f32_e32 v38, v27, v45
	v_add_f32_e32 v37, v37, v38
	s_waitcnt lgkmcnt(1)
	v_mul_f32_e32 v38, v28, v47
	v_fmac_f32_e32 v38, v26, v46
	v_fmac_f32_e32 v38, v33, v48
	v_fmac_f32_e32 v38, v31, v49
	v_add_f32_e32 v37, v37, v38
	s_waitcnt lgkmcnt(0)
	v_mul_f32_e32 v38, v32, v51
	v_fmac_f32_e32 v38, v30, v50
	v_fmac_f32_e32 v38, v34, v52
	v_fmac_f32_e32 v38, v35, v53
	v_add_f32_e32 v37, v37, v38
	v_min_f32_e32 v38, 0, v37
	v_mul_f32_e64 v37, |v37|, s93
	v_exp_f32_e32 v37, v37
	s_nop 0
	v_add_f32_e32 v37, 1.0, v37
	v_cmp_gt_f32_e64 s[62:63], s92, v37
	s_nop 1
	v_cndmask_b32_e64 v39, 0, 32, s[62:63]
	v_ldexp_f32 v37, v37, v39
	v_log_f32_e32 v37, v37
	s_nop 0
	v_mul_f32_e32 v39, 0x3f317217, v37
	v_fma_f32 v39, v37, s1, -v39
	v_fmac_f32_e32 v39, 0x3377d1cf, v37
	v_fmac_f32_e32 v39, 0x3f317217, v37
	v_cmp_lt_f32_e64 s[64:65], |v37|, s72
	s_nop 1
	v_cndmask_b32_e64 v37, v37, v39, s[64:65]
	v_cndmask_b32_e64 v39, 0, v208, s[62:63]
	v_sub_f32_e32 v37, v37, v39
	v_sub_f32_e32 v37, v38, v37
	v_fmac_f32_e32 v36, 0x3d800000, v37
	ds_write_b32 v138, v36 offset:1584
	ds_read_b128 v[38:41], v157
	ds_read_b128 v[42:45], v157 offset:16
	ds_read_b128 v[46:49], v157 offset:32
	ds_read_b128 v[50:53], v157 offset:48
	s_waitcnt lgkmcnt(3)
	v_mul_f32_e32 v37, v22, v39
	v_fmac_f32_e32 v37, v20, v38
	s_waitcnt lgkmcnt(2)
	v_mul_f32_e32 v38, v24, v43
	v_fmac_f32_e32 v37, v25, v40
	v_fmac_f32_e32 v38, v21, v42
	v_fmac_f32_e32 v37, v23, v41
	v_fmac_f32_e32 v38, v29, v44
	v_add_f32_e32 v37, v2, v37
	v_fmac_f32_e32 v38, v27, v45
	v_add_f32_e32 v37, v37, v38
	s_waitcnt lgkmcnt(1)
	v_mul_f32_e32 v38, v28, v47
	v_fmac_f32_e32 v38, v26, v46
	v_fmac_f32_e32 v38, v33, v48
	v_fmac_f32_e32 v38, v31, v49
	v_add_f32_e32 v37, v37, v38
	s_waitcnt lgkmcnt(0)
	v_mul_f32_e32 v38, v32, v51
	v_fmac_f32_e32 v38, v30, v50
	v_fmac_f32_e32 v38, v34, v52
	v_fmac_f32_e32 v38, v35, v53
	v_add_f32_e32 v37, v37, v38
	v_min_f32_e32 v38, 0, v37
	v_mul_f32_e64 v37, |v37|, s93
	v_exp_f32_e32 v37, v37
	s_nop 0
	v_add_f32_e32 v37, 1.0, v37
	v_cmp_gt_f32_e64 s[62:63], s92, v37
	s_nop 1
	v_cndmask_b32_e64 v39, 0, 32, s[62:63]
	v_ldexp_f32 v37, v37, v39
	v_log_f32_e32 v37, v37
	s_nop 0
	v_mul_f32_e32 v39, 0x3f317217, v37
	v_fma_f32 v39, v37, s1, -v39
	v_fmac_f32_e32 v39, 0x3377d1cf, v37
	v_fmac_f32_e32 v39, 0x3f317217, v37
	v_cmp_lt_f32_e64 s[64:65], |v37|, s72
	s_nop 1
	v_cndmask_b32_e64 v37, v37, v39, s[64:65]
	v_cndmask_b32_e64 v39, 0, v208, s[62:63]
	v_sub_f32_e32 v37, v37, v39
	v_sub_f32_e32 v37, v38, v37
	v_fmac_f32_e32 v36, 0x3d800000, v37
	ds_write_b32 v138, v36 offset:2112
	ds_read_b128 v[38:41], v158
	ds_read_b128 v[42:45], v158 offset:16
	ds_read_b128 v[46:49], v158 offset:32
	ds_read_b128 v[50:53], v158 offset:48
	s_waitcnt lgkmcnt(3)
; #define LAS __attribute__((address_space(3)))
; __device__ __forceinline__ void gla_a_unit(LAS unsigned char* lds, bf16* QKA, bf16* VA, const float* FA, unsigned char* ws, int xnrow0, float* DECB, int lchunk, int h,
;                                            const float* wgate, const float* bgate, int tid) {
;     ...
;         float wg[16];
; #pragma unroll
;         for (int r = 0; r < 16; ++r) wg[r] = wgate[r * 512 + h * 128 + gd];
;         const float bg = bgate[h * 128 + gd];
;         float run = 0.f;
; #pragma unroll
;         for (int tt = 0; tt < 16; ++tt) { const int t = tq * 16 + tt; const LAS f32x4* fp = (const LAS f32x4*)(FAi + t * 16); float x = bg;
; #pragma unroll
;             for (int q = 0; q < 4; ++q) { const f32x4 f = fp[q]; x += f[0] * wg[4 * q] + f[1] * wg[4 * q + 1] + f[2] * wg[4 * q + 2] + f[3] * wg[4 * q + 3]; }
;             const float ls = fminf(x, 0.f) - __logf(1.0f + __expf(-fabsf(x))); run += ls * 0.0625f; Bimg[t * GBP + gd] = run;
;             if ((tt & 3) == 3) asm volatile("" ::: "memory"); }
;         SEG[tq * 128 + gd] = run;
	v_mul_f32_e32 v37, v22, v39
	v_fmac_f32_e32 v37, v20, v38
	s_waitcnt lgkmcnt(2)
	v_mul_f32_e32 v38, v24, v43
	v_fmac_f32_e32 v37, v25, v40
	v_fmac_f32_e32 v38, v21, v42
	v_fmac_f32_e32 v37, v23, v41
	v_fmac_f32_e32 v38, v29, v44
	v_add_f32_e32 v37, v2, v37
	v_fmac_f32_e32 v38, v27, v45
	v_add_f32_e32 v37, v37, v38
	s_waitcnt lgkmcnt(1)
	v_mul_f32_e32 v38, v28, v47
	v_fmac_f32_e32 v38, v26, v46
	v_fmac_f32_e32 v38, v33, v48
	v_fmac_f32_e32 v38, v31, v49
	v_add_f32_e32 v37, v37, v38
	s_waitcnt lgkmcnt(0)
	v_mul_f32_e32 v38, v32, v51
	v_fmac_f32_e32 v38, v30, v50
	v_fmac_f32_e32 v38, v34, v52
	v_fmac_f32_e32 v38, v35, v53
	v_add_f32_e32 v37, v37, v38
	v_min_f32_e32 v38, 0, v37
	v_mul_f32_e64 v37, |v37|, s93
	v_exp_f32_e32 v37, v37
	s_nop 0
	v_add_f32_e32 v37, 1.0, v37
	v_cmp_gt_f32_e64 s[62:63], s92, v37
	s_nop 1
	v_cndmask_b32_e64 v39, 0, 32, s[62:63]
	v_ldexp_f32 v37, v37, v39
	v_log_f32_e32 v37, v37
	s_nop 0
	v_mul_f32_e32 v39, 0x3f317217, v37
	v_fma_f32 v39, v37, s1, -v39
	v_fmac_f32_e32 v39, 0x3377d1cf, v37
	v_fmac_f32_e32 v39, 0x3f317217, v37
	v_cmp_lt_f32_e64 s[64:65], |v37|, s72
	s_nop 1
	v_cndmask_b32_e64 v37, v37, v39, s[64:65]
	v_cndmask_b32_e64 v39, 0, v208, s[62:63]
	v_sub_f32_e32 v37, v37, v39
	v_sub_f32_e32 v37, v38, v37
	v_fmac_f32_e32 v36, 0x3d800000, v37
	ds_write_b32 v138, v36 offset:2640
	ds_read_b128 v[38:41], v159
	ds_read_b128 v[42:45], v159 offset:16
	ds_read_b128 v[46:49], v159 offset:32
	ds_read_b128 v[50:53], v159 offset:48
	s_waitcnt lgkmcnt(3)
	v_mul_f32_e32 v37, v22, v39
	v_fmac_f32_e32 v37, v20, v38
	s_waitcnt lgkmcnt(2)
	v_mul_f32_e32 v38, v24, v43
	v_fmac_f32_e32 v37, v25, v40
	v_fmac_f32_e32 v38, v21, v42
	v_fmac_f32_e32 v37, v23, v41
	v_fmac_f32_e32 v38, v29, v44
	v_add_f32_e32 v37, v2, v37
	v_fmac_f32_e32 v38, v27, v45
	v_add_f32_e32 v37, v37, v38
	s_waitcnt lgkmcnt(1)
	v_mul_f32_e32 v38, v28, v47
	v_fmac_f32_e32 v38, v26, v46
	v_fmac_f32_e32 v38, v33, v48
	v_fmac_f32_e32 v38, v31, v49
	v_add_f32_e32 v37, v37, v38
	s_waitcnt lgkmcnt(0)
	v_mul_f32_e32 v38, v32, v51
	v_fmac_f32_e32 v38, v30, v50
	v_fmac_f32_e32 v38, v34, v52
	v_fmac_f32_e32 v38, v35, v53
	v_add_f32_e32 v37, v37, v38
	v_min_f32_e32 v38, 0, v37
	v_mul_f32_e64 v37, |v37|, s93
	v_exp_f32_e32 v37, v37
	s_nop 0
	v_add_f32_e32 v37, 1.0, v37
	v_cmp_gt_f32_e64 s[62:63], s92, v37
	s_nop 1
	v_cndmask_b32_e64 v39, 0, 32, s[62:63]
	v_ldexp_f32 v37, v37, v39
	v_log_f32_e32 v37, v37
	s_nop 0
	v_mul_f32_e32 v39, 0x3f317217, v37
	v_fma_f32 v39, v37, s1, -v39
	v_fmac_f32_e32 v39, 0x3377d1cf, v37
	v_fmac_f32_e32 v39, 0x3f317217, v37
	v_cmp_lt_f32_e64 s[64:65], |v37|, s72
	s_nop 1
	v_cndmask_b32_e64 v37, v37, v39, s[64:65]
	v_cndmask_b32_e64 v39, 0, v208, s[62:63]
	v_sub_f32_e32 v37, v37, v39
	v_sub_f32_e32 v37, v38, v37
	v_fmac_f32_e32 v36, 0x3d800000, v37
	ds_write_b32 v138, v36 offset:3168
	ds_read_b128 v[38:41], v160
	ds_read_b128 v[42:45], v160 offset:16
	ds_read_b128 v[46:49], v160 offset:32
	ds_read_b128 v[50:53], v160 offset:48
	s_waitcnt lgkmcnt(3)
	v_mul_f32_e32 v37, v22, v39
	v_fmac_f32_e32 v37, v20, v38
	s_waitcnt lgkmcnt(2)
	v_mul_f32_e32 v38, v24, v43
	v_fmac_f32_e32 v37, v25, v40
	v_fmac_f32_e32 v38, v21, v42
	v_fmac_f32_e32 v37, v23, v41
	v_fmac_f32_e32 v38, v29, v44
	v_add_f32_e32 v37, v2, v37
	v_fmac_f32_e32 v38, v27, v45
	v_add_f32_e32 v37, v37, v38
	s_waitcnt lgkmcnt(1)
	v_mul_f32_e32 v38, v28, v47
	v_fmac_f32_e32 v38, v26, v46
	v_fmac_f32_e32 v38, v33, v48
	v_fmac_f32_e32 v38, v31, v49
	v_add_f32_e32 v37, v37, v38
	s_waitcnt lgkmcnt(0)
	v_mul_f32_e32 v38, v32, v51
	v_fmac_f32_e32 v38, v30, v50
	v_fmac_f32_e32 v38, v34, v52
	v_fmac_f32_e32 v38, v35, v53
	v_add_f32_e32 v37, v37, v38
	v_min_f32_e32 v38, 0, v37
	v_mul_f32_e64 v37, |v37|, s93
	v_exp_f32_e32 v37, v37
	s_nop 0
	v_add_f32_e32 v37, 1.0, v37
	v_cmp_gt_f32_e64 s[62:63], s92, v37
	s_nop 1
	v_cndmask_b32_e64 v39, 0, 32, s[62:63]
	v_ldexp_f32 v37, v37, v39
	v_log_f32_e32 v37, v37
	s_nop 0
	v_mul_f32_e32 v39, 0x3f317217, v37
	v_fma_f32 v39, v37, s1, -v39
	v_fmac_f32_e32 v39, 0x3377d1cf, v37
	v_fmac_f32_e32 v39, 0x3f317217, v37
	v_cmp_lt_f32_e64 s[64:65], |v37|, s72
	s_nop 1
	v_cndmask_b32_e64 v37, v37, v39, s[64:65]
	v_cndmask_b32_e64 v39, 0, v208, s[62:63]
	v_sub_f32_e32 v37, v37, v39
	v_sub_f32_e32 v37, v38, v37
	v_fmac_f32_e32 v36, 0x3d800000, v37
	ds_write_b32 v138, v36 offset:3696
	ds_read_b128 v[38:41], v161
	ds_read_b128 v[42:45], v161 offset:16
	ds_read_b128 v[46:49], v161 offset:32
	ds_read_b128 v[50:53], v161 offset:48
	s_waitcnt lgkmcnt(3)
	v_mul_f32_e32 v37, v22, v39
	v_fmac_f32_e32 v37, v20, v38
	s_waitcnt lgkmcnt(2)
	v_mul_f32_e32 v38, v24, v43
	v_fmac_f32_e32 v37, v25, v40
	v_fmac_f32_e32 v38, v21, v42
	v_fmac_f32_e32 v37, v23, v41
	v_fmac_f32_e32 v38, v29, v44
	v_add_f32_e32 v37, v2, v37
	v_fmac_f32_e32 v38, v27, v45
	v_add_f32_e32 v37, v37, v38
	s_waitcnt lgkmcnt(1)
	v_mul_f32_e32 v38, v28, v47
	v_fmac_f32_e32 v38, v26, v46
	v_fmac_f32_e32 v38, v33, v48
	v_fmac_f32_e32 v38, v31, v49
	v_add_f32_e32 v37, v37, v38
	s_waitcnt lgkmcnt(0)
	v_mul_f32_e32 v38, v32, v51
	v_fmac_f32_e32 v38, v30, v50
	v_fmac_f32_e32 v38, v34, v52
	v_fmac_f32_e32 v38, v35, v53
	v_add_f32_e32 v37, v37, v38
	v_min_f32_e32 v38, 0, v37
	v_mul_f32_e64 v37, |v37|, s93
	v_exp_f32_e32 v37, v37
	s_nop 0
	v_add_f32_e32 v37, 1.0, v37
	v_cmp_gt_f32_e64 s[62:63], s92, v37
	s_nop 1
	v_cndmask_b32_e64 v39, 0, 32, s[62:63]
	v_ldexp_f32 v37, v37, v39
	v_log_f32_e32 v37, v37
	s_nop 0
	v_mul_f32_e32 v39, 0x3f317217, v37
	v_fma_f32 v39, v37, s1, -v39
	v_fmac_f32_e32 v39, 0x3377d1cf, v37
	v_fmac_f32_e32 v39, 0x3f317217, v37
	v_cmp_lt_f32_e64 s[64:65], |v37|, s72
	s_nop 1
	v_cndmask_b32_e64 v37, v37, v39, s[64:65]
	v_cndmask_b32_e64 v39, 0, v208, s[62:63]
	v_sub_f32_e32 v37, v37, v39
	v_sub_f32_e32 v37, v38, v37
	v_fmac_f32_e32 v36, 0x3d800000, v37
	ds_write_b32 v138, v36 offset:4224
	ds_read_b128 v[38:41], v162
	ds_read_b128 v[42:45], v162 offset:16
	ds_read_b128 v[46:49], v162 offset:32
	ds_read_b128 v[50:53], v162 offset:48
	s_waitcnt lgkmcnt(3)
; #define LAS __attribute__((address_space(3)))
; __device__ __forceinline__ void gla_a_unit(LAS unsigned char* lds, bf16* QKA, bf16* VA, const float* FA, unsigned char* ws, int xnrow0, float* DECB, int lchunk, int h,
;                                            const float* wgate, const float* bgate, int tid) {
;     ...
;         float wg[16];
; #pragma unroll
;         for (int r = 0; r < 16; ++r) wg[r] = wgate[r * 512 + h * 128 + gd];
;         const float bg = bgate[h * 128 + gd];
;         float run = 0.f;
; #pragma unroll
;         for (int tt = 0; tt < 16; ++tt) { const int t = tq * 16 + tt; const LAS f32x4* fp = (const LAS f32x4*)(FAi + t * 16); float x = bg;
; #pragma unroll
;             for (int q = 0; q < 4; ++q) { const f32x4 f = fp[q]; x += f[0] * wg[4 * q] + f[1] * wg[4 * q + 1] + f[2] * wg[4 * q + 2] + f[3] * wg[4 * q + 3]; }
;             const float ls = fminf(x, 0.f) - __logf(1.0f + __expf(-fabsf(x))); run += ls * 0.0625f; Bimg[t * GBP + gd] = run;
;             if ((tt & 3) == 3) asm volatile("" ::: "memory"); }
;         SEG[tq * 128 + gd] = run;
	v_mul_f32_e32 v37, v22, v39
	v_fmac_f32_e32 v37, v20, v38
	s_waitcnt lgkmcnt(2)
	v_mul_f32_e32 v38, v24, v43
	v_fmac_f32_e32 v37, v25, v40
	v_fmac_f32_e32 v38, v21, v42
	v_fmac_f32_e32 v37, v23, v41
	v_fmac_f32_e32 v38, v29, v44
	v_add_f32_e32 v37, v2, v37
	v_fmac_f32_e32 v38, v27, v45
	v_add_f32_e32 v37, v37, v38
	s_waitcnt lgkmcnt(1)
	v_mul_f32_e32 v38, v28, v47
	v_fmac_f32_e32 v38, v26, v46
	v_fmac_f32_e32 v38, v33, v48
	v_fmac_f32_e32 v38, v31, v49
	v_add_f32_e32 v37, v37, v38
	s_waitcnt lgkmcnt(0)
	v_mul_f32_e32 v38, v32, v51
	v_fmac_f32_e32 v38, v30, v50
	v_fmac_f32_e32 v38, v34, v52
	v_fmac_f32_e32 v38, v35, v53
	v_add_f32_e32 v37, v37, v38
	v_min_f32_e32 v38, 0, v37
	v_mul_f32_e64 v37, |v37|, s93
	v_exp_f32_e32 v37, v37
	s_nop 0
	v_add_f32_e32 v37, 1.0, v37
	v_cmp_gt_f32_e64 s[62:63], s92, v37
	s_nop 1
	v_cndmask_b32_e64 v39, 0, 32, s[62:63]
	v_ldexp_f32 v37, v37, v39
	v_log_f32_e32 v37, v37
	s_nop 0
	v_mul_f32_e32 v39, 0x3f317217, v37
	v_fma_f32 v39, v37, s1, -v39
	v_fmac_f32_e32 v39, 0x3377d1cf, v37
	v_fmac_f32_e32 v39, 0x3f317217, v37
	v_cmp_lt_f32_e64 s[64:65], |v37|, s72
	s_nop 1
	v_cndmask_b32_e64 v37, v37, v39, s[64:65]
	v_cndmask_b32_e64 v39, 0, v208, s[62:63]
	v_sub_f32_e32 v37, v37, v39
	v_sub_f32_e32 v37, v38, v37
	v_fmac_f32_e32 v36, 0x3d800000, v37
	ds_write_b32 v138, v36 offset:4752
	ds_read_b128 v[38:41], v163
	ds_read_b128 v[42:45], v163 offset:16
	ds_read_b128 v[46:49], v163 offset:32
	ds_read_b128 v[50:53], v163 offset:48
	s_waitcnt lgkmcnt(3)
	v_mul_f32_e32 v37, v22, v39
	v_fmac_f32_e32 v37, v20, v38
	s_waitcnt lgkmcnt(2)
	v_mul_f32_e32 v38, v24, v43
	v_fmac_f32_e32 v37, v25, v40
	v_fmac_f32_e32 v38, v21, v42
	v_fmac_f32_e32 v37, v23, v41
	v_fmac_f32_e32 v38, v29, v44
	v_add_f32_e32 v37, v2, v37
	v_fmac_f32_e32 v38, v27, v45
	v_add_f32_e32 v37, v37, v38
	s_waitcnt lgkmcnt(1)
	v_mul_f32_e32 v38, v28, v47
	v_fmac_f32_e32 v38, v26, v46
	v_fmac_f32_e32 v38, v33, v48
	v_fmac_f32_e32 v38, v31, v49
	v_add_f32_e32 v37, v37, v38
	s_waitcnt lgkmcnt(0)
	v_mul_f32_e32 v38, v32, v51
	v_fmac_f32_e32 v38, v30, v50
	v_fmac_f32_e32 v38, v34, v52
	v_fmac_f32_e32 v38, v35, v53
	v_add_f32_e32 v37, v37, v38
	v_min_f32_e32 v38, 0, v37
	v_mul_f32_e64 v37, |v37|, s93
	v_exp_f32_e32 v37, v37
	s_nop 0
	v_add_f32_e32 v37, 1.0, v37
	v_cmp_gt_f32_e64 s[62:63], s92, v37
	s_nop 1
	v_cndmask_b32_e64 v39, 0, 32, s[62:63]
	v_ldexp_f32 v37, v37, v39
	v_log_f32_e32 v37, v37
	s_nop 0
	v_mul_f32_e32 v39, 0x3f317217, v37
	v_fma_f32 v39, v37, s1, -v39
	v_fmac_f32_e32 v39, 0x3377d1cf, v37
	v_fmac_f32_e32 v39, 0x3f317217, v37
	v_cmp_lt_f32_e64 s[64:65], |v37|, s72
	s_nop 1
	v_cndmask_b32_e64 v37, v37, v39, s[64:65]
	v_cndmask_b32_e64 v39, 0, v208, s[62:63]
	v_sub_f32_e32 v37, v37, v39
	v_sub_f32_e32 v37, v38, v37
	v_fmac_f32_e32 v36, 0x3d800000, v37
	ds_write_b32 v138, v36 offset:5280
	ds_read_b128 v[38:41], v164
	ds_read_b128 v[42:45], v164 offset:16
	ds_read_b128 v[46:49], v164 offset:32
	ds_read_b128 v[50:53], v164 offset:48
	s_waitcnt lgkmcnt(3)
	v_mul_f32_e32 v37, v22, v39
	v_fmac_f32_e32 v37, v20, v38
	s_waitcnt lgkmcnt(2)
	v_mul_f32_e32 v38, v24, v43
	v_fmac_f32_e32 v37, v25, v40
	v_fmac_f32_e32 v38, v21, v42
	v_fmac_f32_e32 v37, v23, v41
	v_fmac_f32_e32 v38, v29, v44
	v_add_f32_e32 v37, v2, v37
	v_fmac_f32_e32 v38, v27, v45
	v_add_f32_e32 v37, v37, v38
	s_waitcnt lgkmcnt(1)
	v_mul_f32_e32 v38, v28, v47
	v_fmac_f32_e32 v38, v26, v46
	v_fmac_f32_e32 v38, v33, v48
	v_fmac_f32_e32 v38, v31, v49
	v_add_f32_e32 v37, v37, v38
	s_waitcnt lgkmcnt(0)
	v_mul_f32_e32 v38, v32, v51
	v_fmac_f32_e32 v38, v30, v50
	v_fmac_f32_e32 v38, v34, v52
	v_fmac_f32_e32 v38, v35, v53
	v_add_f32_e32 v37, v37, v38
	v_min_f32_e32 v38, 0, v37
	v_mul_f32_e64 v37, |v37|, s93
	v_exp_f32_e32 v37, v37
	s_nop 0
	v_add_f32_e32 v37, 1.0, v37
	v_cmp_gt_f32_e64 s[62:63], s92, v37
	s_nop 1
	v_cndmask_b32_e64 v39, 0, 32, s[62:63]
	v_ldexp_f32 v37, v37, v39
	v_log_f32_e32 v37, v37
	s_nop 0
	v_mul_f32_e32 v39, 0x3f317217, v37
	v_fma_f32 v39, v37, s1, -v39
	v_fmac_f32_e32 v39, 0x3377d1cf, v37
	v_fmac_f32_e32 v39, 0x3f317217, v37
	v_cmp_lt_f32_e64 s[64:65], |v37|, s72
	s_nop 1
	v_cndmask_b32_e64 v37, v37, v39, s[64:65]
	v_cndmask_b32_e64 v39, 0, v208, s[62:63]
	v_sub_f32_e32 v37, v37, v39
	v_sub_f32_e32 v37, v38, v37
	v_fmac_f32_e32 v36, 0x3d800000, v37
	ds_write_b32 v138, v36 offset:5808
	ds_read_b128 v[38:41], v165
	ds_read_b128 v[42:45], v165 offset:16
	ds_read_b128 v[46:49], v165 offset:32
	ds_read_b128 v[50:53], v165 offset:48
	s_waitcnt lgkmcnt(3)
	v_mul_f32_e32 v37, v22, v39
	v_fmac_f32_e32 v37, v20, v38
	s_waitcnt lgkmcnt(2)
	v_mul_f32_e32 v38, v24, v43
	v_fmac_f32_e32 v37, v25, v40
	v_fmac_f32_e32 v38, v21, v42
	v_fmac_f32_e32 v37, v23, v41
	v_fmac_f32_e32 v38, v29, v44
	v_add_f32_e32 v37, v2, v37
	v_fmac_f32_e32 v38, v27, v45
	v_add_f32_e32 v37, v37, v38
	s_waitcnt lgkmcnt(1)
	v_mul_f32_e32 v38, v28, v47
	v_fmac_f32_e32 v38, v26, v46
	v_fmac_f32_e32 v38, v33, v48
	v_fmac_f32_e32 v38, v31, v49
	v_add_f32_e32 v37, v37, v38
	s_waitcnt lgkmcnt(0)
	v_mul_f32_e32 v38, v32, v51
	v_fmac_f32_e32 v38, v30, v50
	v_fmac_f32_e32 v38, v34, v52
	v_fmac_f32_e32 v38, v35, v53
	v_add_f32_e32 v37, v37, v38
	v_min_f32_e32 v38, 0, v37
	v_mul_f32_e64 v37, |v37|, s93
	v_exp_f32_e32 v37, v37
	s_nop 0
	v_add_f32_e32 v37, 1.0, v37
	v_cmp_gt_f32_e64 s[62:63], s92, v37
	s_nop 1
	v_cndmask_b32_e64 v39, 0, 32, s[62:63]
	v_ldexp_f32 v37, v37, v39
	v_log_f32_e32 v37, v37
	s_nop 0
	v_mul_f32_e32 v39, 0x3f317217, v37
	v_fma_f32 v39, v37, s1, -v39
	v_fmac_f32_e32 v39, 0x3377d1cf, v37
	v_fmac_f32_e32 v39, 0x3f317217, v37
	v_cmp_lt_f32_e64 s[64:65], |v37|, s72
	s_nop 1
	v_cndmask_b32_e64 v37, v37, v39, s[64:65]
	v_cndmask_b32_e64 v39, 0, v208, s[62:63]
	v_sub_f32_e32 v37, v37, v39
	v_sub_f32_e32 v37, v38, v37
	v_fmac_f32_e32 v36, 0x3d800000, v37
	ds_write_b32 v138, v36 offset:6336
	ds_read_b128 v[38:41], v166
	ds_read_b128 v[42:45], v166 offset:16
	ds_read_b128 v[46:49], v166 offset:32
	ds_read_b128 v[50:53], v166 offset:48
	s_waitcnt lgkmcnt(3)
; #define LAS __attribute__((address_space(3)))
; __device__ __forceinline__ void gla_a_unit(LAS unsigned char* lds, bf16* QKA, bf16* VA, const float* FA, unsigned char* ws, int xnrow0, float* DECB, int lchunk, int h,
;                                            const float* wgate, const float* bgate, int tid) {
;     ...
;         for (int tt = 0; tt < 16; ++tt) { const int t = tq * 16 + tt; const LAS f32x4* fp = (const LAS f32x4*)(FAi + t * 16); float x = bg;
; #pragma unroll
;             for (int q = 0; q < 4; ++q) { const f32x4 f = fp[q]; x += f[0] * wg[4 * q] + f[1] * wg[4 * q + 1] + f[2] * wg[4 * q + 2] + f[3] * wg[4 * q + 3]; }
;             const float ls = fminf(x, 0.f) - __logf(1.0f + __expf(-fabsf(x))); run += ls * 0.0625f; Bimg[t * GBP + gd] = run;
;             if ((tt & 3) == 3) asm volatile("" ::: "memory"); }
;         SEG[tq * 128 + gd] = run;
;     }
;     __syncthreads();
; #pragma unroll
;     for (int i = 0; i < 2; ++i) { const int id = tid + 512 * i, row = id >> 4, ch = id & 15;
;         f32x4 b0 = *(const LAS f32x4*)(Bimg + row * GBP + ch * 8), b1 = *(const LAS f32x4*)(Bimg + row * GBP + ch * 8 + 4);
;         f32x4 l0 = (f32x4){0.f, 0.f, 0.f, 0.f}, l1 = l0;
; #pragma unroll
;         for (int q = 0; q < 4; ++q) { const f32x4 s0v = *(const LAS f32x4*)(SEG + q * 128 + ch * 8), s1v = *(const LAS f32x4*)(SEG + q * 128 + ch * 8 + 4);
;             l0 += s0v; l1 += s1v; if (q < (row >> 4)) { b0 += s0v; b1 += s1v; } }
;         if (row == 0) { float* dp = DECB + (size_t)unit * 128 + ch * 8;
;             *(f32x4*)dp = (f32x4){__expf(l0[0]), __expf(l0[1]), __expf(l0[2]), __expf(l0[3])}; *(f32x4*)(dp + 4) = (f32x4){__expf(l1[0]), __expf(l1[1]), __expf(l1[2]), __expf(l1[3])}; }
	v_mul_f32_e32 v37, v22, v39
	v_fmac_f32_e32 v37, v20, v38
	s_waitcnt lgkmcnt(2)
	v_mul_f32_e32 v38, v24, v43
	v_fmac_f32_e32 v37, v25, v40
	v_fmac_f32_e32 v38, v21, v42
	v_fmac_f32_e32 v37, v23, v41
	v_fmac_f32_e32 v38, v29, v44
	v_add_f32_e32 v37, v2, v37
	v_fmac_f32_e32 v38, v27, v45
	v_add_f32_e32 v37, v37, v38
	s_waitcnt lgkmcnt(1)
	v_mul_f32_e32 v38, v28, v47
	v_fmac_f32_e32 v38, v26, v46
	v_fmac_f32_e32 v38, v33, v48
	v_fmac_f32_e32 v38, v31, v49
	v_add_f32_e32 v37, v37, v38
	s_waitcnt lgkmcnt(0)
	v_mul_f32_e32 v38, v32, v51
	v_fmac_f32_e32 v38, v30, v50
	v_fmac_f32_e32 v38, v34, v52
	v_fmac_f32_e32 v38, v35, v53
	v_add_f32_e32 v37, v37, v38
	v_min_f32_e32 v38, 0, v37
	v_mul_f32_e64 v37, |v37|, s93
	v_exp_f32_e32 v37, v37
	s_nop 0
	v_add_f32_e32 v37, 1.0, v37
	v_cmp_gt_f32_e64 s[62:63], s92, v37
	s_nop 1
	v_cndmask_b32_e64 v39, 0, 32, s[62:63]
	v_ldexp_f32 v37, v37, v39
	v_log_f32_e32 v37, v37
	s_nop 0
	v_mul_f32_e32 v39, 0x3f317217, v37
	v_fma_f32 v39, v37, s1, -v39
	v_fmac_f32_e32 v39, 0x3377d1cf, v37
	v_fmac_f32_e32 v39, 0x3f317217, v37
	v_cmp_lt_f32_e64 s[64:65], |v37|, s72
	s_nop 1
	v_cndmask_b32_e64 v37, v37, v39, s[64:65]
	v_cndmask_b32_e64 v39, 0, v208, s[62:63]
	v_sub_f32_e32 v37, v37, v39
	v_sub_f32_e32 v37, v38, v37
	v_fmac_f32_e32 v36, 0x3d800000, v37
	ds_write_b32 v138, v36 offset:6864
	ds_read_b128 v[38:41], v167
	ds_read_b128 v[42:45], v167 offset:16
	ds_read_b128 v[46:49], v167 offset:32
	ds_read_b128 v[50:53], v167 offset:48
	s_waitcnt lgkmcnt(3)
	v_mul_f32_e32 v37, v22, v39
	v_fmac_f32_e32 v37, v20, v38
	s_waitcnt lgkmcnt(2)
	v_mul_f32_e32 v38, v24, v43
	v_fmac_f32_e32 v37, v25, v40
	v_fmac_f32_e32 v38, v21, v42
	v_fmac_f32_e32 v37, v23, v41
	v_fmac_f32_e32 v38, v29, v44
	v_add_f32_e32 v37, v2, v37
	v_fmac_f32_e32 v38, v27, v45
	v_add_f32_e32 v37, v37, v38
	s_waitcnt lgkmcnt(1)
	v_mul_f32_e32 v38, v28, v47
	v_fmac_f32_e32 v38, v26, v46
	v_fmac_f32_e32 v38, v33, v48
	v_fmac_f32_e32 v38, v31, v49
	v_add_f32_e32 v37, v37, v38
	s_waitcnt lgkmcnt(0)
	v_mul_f32_e32 v38, v32, v51
	v_fmac_f32_e32 v38, v30, v50
	v_fmac_f32_e32 v38, v34, v52
	v_fmac_f32_e32 v38, v35, v53
	v_add_f32_e32 v37, v37, v38
	v_min_f32_e32 v38, 0, v37
	v_mul_f32_e64 v37, |v37|, s93
	v_exp_f32_e32 v37, v37
	s_nop 0
	v_add_f32_e32 v37, 1.0, v37
	v_cmp_gt_f32_e64 s[62:63], s92, v37
	s_nop 1
	v_cndmask_b32_e64 v39, 0, 32, s[62:63]
	v_ldexp_f32 v37, v37, v39
	v_log_f32_e32 v37, v37
	s_nop 0
	v_mul_f32_e32 v39, 0x3f317217, v37
	v_fma_f32 v39, v37, s1, -v39
	v_fmac_f32_e32 v39, 0x3377d1cf, v37
	v_fmac_f32_e32 v39, 0x3f317217, v37
	v_cmp_lt_f32_e64 s[64:65], |v37|, s72
	s_nop 1
	v_cndmask_b32_e64 v37, v37, v39, s[64:65]
	v_cndmask_b32_e64 v39, 0, v208, s[62:63]
	v_sub_f32_e32 v37, v37, v39
	v_sub_f32_e32 v37, v38, v37
	v_fmac_f32_e32 v36, 0x3d800000, v37
	ds_write_b32 v138, v36 offset:7392
	ds_read_b128 v[38:41], v168
	ds_read_b128 v[42:45], v168 offset:16
	ds_read_b128 v[46:49], v168 offset:32
	ds_read_b128 v[50:53], v168 offset:48
	s_waitcnt lgkmcnt(3)
	v_mul_f32_e32 v22, v22, v39
	v_fmac_f32_e32 v22, v20, v38
	s_waitcnt lgkmcnt(2)
	v_mul_f32_e32 v20, v24, v43
	v_fmac_f32_e32 v22, v25, v40
	v_fmac_f32_e32 v20, v21, v42
	v_fmac_f32_e32 v22, v23, v41
	v_fmac_f32_e32 v20, v29, v44
	v_add_f32_e32 v2, v2, v22
	v_fmac_f32_e32 v20, v27, v45
	v_add_f32_e32 v2, v2, v20
	s_waitcnt lgkmcnt(1)
	v_mul_f32_e32 v20, v28, v47
	v_fmac_f32_e32 v20, v26, v46
	v_fmac_f32_e32 v20, v33, v48
	v_fmac_f32_e32 v20, v31, v49
	v_add_f32_e32 v2, v2, v20
	s_waitcnt lgkmcnt(0)
	v_mul_f32_e32 v20, v32, v51
	v_fmac_f32_e32 v20, v30, v50
	v_fmac_f32_e32 v20, v34, v52
	v_fmac_f32_e32 v20, v35, v53
	v_add_f32_e32 v2, v2, v20
	v_min_f32_e32 v20, 0, v2
	v_mul_f32_e64 v2, |v2|, s93
	v_exp_f32_e32 v2, v2
	s_nop 0
	v_add_f32_e32 v2, 1.0, v2
	v_cmp_gt_f32_e64 s[62:63], s92, v2
	s_nop 1
	v_cndmask_b32_e64 v21, 0, 32, s[62:63]
	v_ldexp_f32 v2, v2, v21
	v_log_f32_e32 v2, v2
	s_nop 0
	v_mul_f32_e32 v21, 0x3f317217, v2
	v_fma_f32 v21, v2, s1, -v21
	v_fmac_f32_e32 v21, 0x3377d1cf, v2
	v_fmac_f32_e32 v21, 0x3f317217, v2
	v_cmp_lt_f32_e64 s[64:65], |v2|, s72
	s_nop 1
	v_cndmask_b32_e64 v2, v2, v21, s[64:65]
	v_cndmask_b32_e64 v21, 0, v208, s[62:63]
	v_sub_f32_e32 v2, v2, v21
	v_sub_f32_e32 v2, v20, v2
	v_fmac_f32_e32 v36, 0x3d800000, v2
	v_lshl_add_u64 v[20:21], v[122:123], 0, s[88:89]
	ds_write_b32 v139, v36
	v_lshl_add_u64 v[66:67], v[20:21], 0, s[6:7]
	s_mov_b64 s[6:7], 0x4200010
	ds_write_b32 v129, v36
	s_waitcnt lgkmcnt(0)
	s_barrier
	v_lshl_add_u64 v[64:65], v[20:21], 0, s[6:7]
	ds_read_b128 v[44:47], v146
	ds_read_b128 v[48:51], v146 offset:16
	ds_read_b128 v[56:59], v130
	ds_read_b128 v[52:55], v130 offset:16
	ds_read_b128 v[40:43], v130 offset:512
	ds_read_b128 v[36:39], v130 offset:528
	ds_read_b128 v[32:35], v130 offset:1024
	ds_read_b128 v[28:31], v130 offset:1040
	ds_read_b128 v[24:27], v130 offset:1536
	ds_read_b128 v[20:23], v130 offset:1552
	s_and_saveexec_b64 s[62:63], s[16:17]
	s_cbranch_execz .LBB0_562
	s_waitcnt lgkmcnt(6)
	v_pk_add_f32 v[68:69], v[54:55], 0 op_sel_hi:[1,0]
	v_pk_add_f32 v[70:71], v[52:53], 0 op_sel_hi:[1,0]
	s_waitcnt lgkmcnt(4)
	v_pk_add_f32 v[68:69], v[68:69], v[38:39]
	v_pk_add_f32 v[70:71], v[70:71], v[36:37]
	s_waitcnt lgkmcnt(2)
	v_pk_add_f32 v[68:69], v[68:69], v[30:31]
	v_pk_add_f32 v[70:71], v[70:71], v[28:29]
	s_waitcnt lgkmcnt(0)
	v_pk_add_f32 v[74:75], v[68:69], v[22:23]
	v_pk_add_f32 v[72:73], v[70:71], v[20:21]
	v_pk_add_f32 v[68:69], v[58:59], 0 op_sel_hi:[1,0]
	v_pk_add_f32 v[70:71], v[56:57], 0 op_sel_hi:[1,0]
	v_pk_add_f32 v[68:69], v[68:69], v[42:43]
	v_pk_add_f32 v[70:71], v[70:71], v[40:41]
	v_pk_add_f32 v[68:69], v[68:69], v[34:35]
	v_pk_add_f32 v[70:71], v[70:71], v[32:33]
	v_pk_add_f32 v[76:77], v[68:69], v[26:27]
	v_pk_add_f32 v[68:69], v[70:71], v[24:25]
	s_nop 0
	v_mul_f32_e32 v2, 0x3fb8aa3b, v68
	v_exp_f32_e32 v68, v2
	v_mul_f32_e32 v2, 0x3fb8aa3b, v69
	v_exp_f32_e32 v69, v2
	v_mul_f32_e32 v2, 0x3fb8aa3b, v76
	v_exp_f32_e32 v70, v2
	v_mul_f32_e32 v2, 0x3fb8aa3b, v77
	v_exp_f32_e32 v71, v2
	v_mul_f32_e32 v2, 0x3fb8aa3b, v72
	v_exp_f32_e32 v72, v2
	v_mul_f32_e32 v2, 0x3fb8aa3b, v73
	v_exp_f32_e32 v73, v2
	v_mul_f32_e32 v2, 0x3fb8aa3b, v74
	v_exp_f32_e32 v74, v2
	v_mul_f32_e32 v2, 0x3fb8aa3b, v75
	v_exp_f32_e32 v75, v2
	global_store_dwordx4 v[66:67], v[68:71], off
	global_store_dwordx4 v[64:65], v[72:75], off
